# final norm phase rewritten by hand: gains loaded once, next row prefetched, DPP+readlane reduction; on top of the 2-rows-per-lane scanner
# speedup vs baseline: 1.0076x; 1.0026x over previous
; #define GAS __attribute__((address_space(1)))
;     __device__ __forceinline__ void ids() { lane = fresh_lane(); tid = wave * 64 + lane; }
; __device__ __forceinline__ f32x4 up4(const v2u w) { return (f32x4){bfl(w.x), bfh(w.x), bfl(w.y), bfh(w.y)}; }
; #define ws ((unsigned char*)in_ptr(F, T_WS))
; #define XO ((float*)in_ptr(F, T_OUT))
; #define INP(i) in_ptr(F, (i))
; __device__ __forceinline__ void final_norm_phase(Frame& F, const bf16* XH, float* OUT, const float* gn) {
;     F.ids();
;     const int gw = F.vcu * NWAVES + F.wave, NGW = F.G * NWAVES, lane = F.lane;
; #pragma unroll 2
;     for (int m = gw; m < M; m += NGW) {
;         const GAS v2u* hp = (const GAS v2u*)(XH + (size_t)m * D) + lane;
;         GAS f32x4* xr = (GAS f32x4*)(OUT + (size_t)m * D) + lane; const GAS f32x4* g4 = (const GAS f32x4*)gn + lane;
;         f32x4 v[8]; float s = 0.f;
; #pragma unroll
;         for (int j = 0; j < 8; ++j) { v[j] = up4(hp[64 * j]); s += (v[j][0] * v[j][0] + v[j][1] * v[j][1]) + (v[j][2] * v[j][2] + v[j][3] * v[j][3]); }
; __global__ void __launch_bounds__(NTHR, 2) mega_fwd(Params P) {
;     ...
;     if (IN(NPH - 1)) final_norm_phase(F, (const bf16*)(ws + WS_XB) + (size_t)((3 * DEPTH) & 1) * M * D, XO, INP(I_FINAL_NORM));
.LBB0_4100:
	s_cmp_lt_i32 s56, 43
	s_cselect_b64 s[0:1], -1, 0
	s_cmp_gt_i32 s57, 42
	s_cselect_b64 s[2:3], -1, 0
	s_and_b64 s[0:1], s[0:1], s[2:3]
	s_andn2_b64 vcc, exec, s[0:1]
	s_cbranch_vccnz .LBB0_4104
	s_add_i32 s0, 0, 0x20520
	v_mov_b32_e32 v0, s0
	s_add_i32 s0, 0, 0x20510
	s_waitcnt lgkmcnt(6)
	ds_read_b64 v[4:5], v0
	v_mov_b32_e32 v0, s0
	s_waitcnt lgkmcnt(1)
	ds_read_b128 v[0:3], v0
	s_lshl_b32 s0, s96, 3
	s_add_i32 s0, s0, s80
	s_waitcnt lgkmcnt(1)
	v_readfirstlane_b32 s6, v4
	v_readfirstlane_b32 s7, v5
	s_waitcnt lgkmcnt(0)
	v_readfirstlane_b32 s3, v2
	v_readfirstlane_b32 s8, v3
	v_readfirstlane_b32 s4, v0
	v_readfirstlane_b32 s5, v1
	s_cmpk_gt_i32 s0, 0x1fff
	v_mbcnt_lo_u32_b32 v12, -1, 0
	v_mbcnt_hi_u32_b32 v12, -1, v12
	s_cbranch_scc1 .LBB0_4104
	v_lshlrev_b32_e32 v1, 3, v12
	v_lshlrev_b32_e32 v2, 4, v12
	s_lshl_b32 s2, s52, 3
	s_add_u32 s4, s4, 0x1000
	s_addc_u32 s5, s5, 0
	global_load_dwordx4 v[100:103], v2, s[4:5] offset:-4096
	global_load_dwordx4 v[104:107], v2, s[4:5] offset:-3072
	global_load_dwordx4 v[108:111], v2, s[4:5] offset:-2048
	global_load_dwordx4 v[112:115], v2, s[4:5] offset:-1024
	global_load_dwordx4 v[116:119], v2, s[4:5] offset:0
	global_load_dwordx4 v[120:123], v2, s[4:5] offset:1024
	global_load_dwordx4 v[124:127], v2, s[4:5] offset:2048
	global_load_dwordx4 v[128:131], v2, s[4:5] offset:3072
	s_ashr_i32 s1, s0, 31
	s_lshl_b64 s[10:11], s[0:1], 12
	s_add_u32 s12, s6, s10
	s_addc_u32 s13, s7, s11
	s_add_u32 s12, s12, 0x21300000
	s_addc_u32 s13, s13, 0
	s_lshl_b64 s[10:11], s[0:1], 13
	s_add_u32 s14, s3, s10
	s_addc_u32 s15, s8, s11
	s_add_u32 s14, s14, 0x1000
	s_addc_u32 s15, s15, 0
	s_mov_b32 s3, 0
	s_lshl_b64 s[16:17], s[2:3], 12
	s_lshl_b64 s[18:19], s[2:3], 13
	global_load_dwordx2 v[140:141], v1, s[12:13] offset:0
	global_load_dwordx2 v[142:143], v1, s[12:13] offset:512
	global_load_dwordx2 v[144:145], v1, s[12:13] offset:1024
	global_load_dwordx2 v[146:147], v1, s[12:13] offset:1536
	global_load_dwordx2 v[148:149], v1, s[12:13] offset:2048
	global_load_dwordx2 v[150:151], v1, s[12:13] offset:2560
	global_load_dwordx2 v[152:153], v1, s[12:13] offset:3072
	global_load_dwordx2 v[154:155], v1, s[12:13] offset:3584
	v_mov_b32_e32 v20, 0x358637bd
	s_waitcnt vmcnt(0)
.Lfn_loop:
	v_lshlrev_b32_e32 v26, 16, v140
	v_and_b32_e32 v27, 0xffff0000, v140
	v_lshlrev_b32_e32 v28, 16, v141
	v_and_b32_e32 v29, 0xffff0000, v141
	v_lshlrev_b32_e32 v30, 16, v142
	v_and_b32_e32 v31, 0xffff0000, v142
	v_lshlrev_b32_e32 v32, 16, v143
	v_and_b32_e32 v33, 0xffff0000, v143
	v_lshlrev_b32_e32 v34, 16, v144
	v_and_b32_e32 v35, 0xffff0000, v144
	v_lshlrev_b32_e32 v36, 16, v145
	v_and_b32_e32 v37, 0xffff0000, v145
	v_lshlrev_b32_e32 v38, 16, v146
	v_and_b32_e32 v39, 0xffff0000, v146
	v_lshlrev_b32_e32 v40, 16, v147
	v_and_b32_e32 v41, 0xffff0000, v147
	v_lshlrev_b32_e32 v42, 16, v148
	v_and_b32_e32 v43, 0xffff0000, v148
	v_lshlrev_b32_e32 v44, 16, v149
	v_and_b32_e32 v45, 0xffff0000, v149
	v_lshlrev_b32_e32 v46, 16, v150
	v_and_b32_e32 v47, 0xffff0000, v150
	v_lshlrev_b32_e32 v48, 16, v151
	v_and_b32_e32 v49, 0xffff0000, v151
	v_lshlrev_b32_e32 v50, 16, v152
	v_and_b32_e32 v51, 0xffff0000, v152
	v_lshlrev_b32_e32 v52, 16, v153
	v_and_b32_e32 v53, 0xffff0000, v153
	v_lshlrev_b32_e32 v54, 16, v154
	v_and_b32_e32 v55, 0xffff0000, v154
	v_lshlrev_b32_e32 v56, 16, v155
	v_and_b32_e32 v57, 0xffff0000, v155
	s_add_i32 s0, s0, s2
	s_add_u32 s12, s12, s16
	s_addc_u32 s13, s13, s17
	s_cmpk_lt_i32 s0, 0x2000
	s_cbranch_scc0 .Lfn_nopf
	global_load_dwordx2 v[140:141], v1, s[12:13] offset:0
	global_load_dwordx2 v[142:143], v1, s[12:13] offset:512
	global_load_dwordx2 v[144:145], v1, s[12:13] offset:1024
	global_load_dwordx2 v[146:147], v1, s[12:13] offset:1536
	global_load_dwordx2 v[148:149], v1, s[12:13] offset:2048
	global_load_dwordx2 v[150:151], v1, s[12:13] offset:2560
	global_load_dwordx2 v[152:153], v1, s[12:13] offset:3072
	global_load_dwordx2 v[154:155], v1, s[12:13] offset:3584
; #define GAS __attribute__((address_space(1)))
; __device__ __forceinline__ f32x4 up4(const v2u w) { return (f32x4){bfl(w.x), bfh(w.x), bfl(w.y), bfh(w.y)}; }
; __device__ __forceinline__ void final_norm_phase(Frame& F, const bf16* XH, float* OUT, const float* gn) {
;     ...
;     for (int m = gw; m < M; m += NGW) {
;         const GAS v2u* hp = (const GAS v2u*)(XH + (size_t)m * D) + lane;
;         GAS f32x4* xr = (GAS f32x4*)(OUT + (size_t)m * D) + lane; const GAS f32x4* g4 = (const GAS f32x4*)gn + lane;
;         f32x4 v[8]; float s = 0.f;
; #pragma unroll
;         for (int j = 0; j < 8; ++j) { v[j] = up4(hp[64 * j]); s += (v[j][0] * v[j][0] + v[j][1] * v[j][1]) + (v[j][2] * v[j][2] + v[j][3] * v[j][3]); }
;         const float rs = __builtin_amdgcn_rsqf(wave_sum(s) * (1.0f / D) + 1e-6f);
; #pragma unroll
;         for (int j = 0; j < 8; ++j) xr[64 * j] = v[j] * rs * g4[64 * j];
.Lfn_nopf:
	v_pk_mul_f32 v[60:61], v[26:27], v[26:27]
	v_pk_mul_f32 v[62:63], v[28:29], v[28:29]
	v_pk_fma_f32 v[60:61], v[30:31], v[30:31], v[60:61]
	v_pk_fma_f32 v[62:63], v[32:33], v[32:33], v[62:63]
	v_pk_fma_f32 v[60:61], v[34:35], v[34:35], v[60:61]
	v_pk_fma_f32 v[62:63], v[36:37], v[36:37], v[62:63]
	v_pk_fma_f32 v[60:61], v[38:39], v[38:39], v[60:61]
	v_pk_fma_f32 v[62:63], v[40:41], v[40:41], v[62:63]
	v_pk_fma_f32 v[60:61], v[42:43], v[42:43], v[60:61]
	v_pk_fma_f32 v[62:63], v[44:45], v[44:45], v[62:63]
	v_pk_fma_f32 v[60:61], v[46:47], v[46:47], v[60:61]
	v_pk_fma_f32 v[62:63], v[48:49], v[48:49], v[62:63]
	v_pk_fma_f32 v[60:61], v[50:51], v[50:51], v[60:61]
	v_pk_fma_f32 v[62:63], v[52:53], v[52:53], v[62:63]
	v_pk_fma_f32 v[60:61], v[54:55], v[54:55], v[60:61]
	v_pk_fma_f32 v[62:63], v[56:57], v[56:57], v[62:63]
	v_pk_add_f32 v[60:61], v[60:61], v[62:63]
	v_add_f32_e32 v21, v60, v61
	s_nop 1
	v_add_f32_dpp v21, v21, v21 quad_perm:[1,0,3,2] row_mask:0xf bank_mask:0xf bound_ctrl:1
	s_nop 1
	v_add_f32_dpp v21, v21, v21 quad_perm:[2,3,0,1] row_mask:0xf bank_mask:0xf bound_ctrl:1
	s_nop 1
	v_add_f32_dpp v21, v21, v21 row_half_mirror row_mask:0xf bank_mask:0xf bound_ctrl:1
	s_nop 1
	v_add_f32_dpp v21, v21, v21 row_mirror row_mask:0xf bank_mask:0xf bound_ctrl:1
	s_nop 1
	v_readlane_b32 s20, v21, 0
	v_readlane_b32 s21, v21, 16
	v_readlane_b32 s22, v21, 32
	v_readlane_b32 s23, v21, 48
	s_nop 1
	v_mov_b32_e32 v22, s20
	v_add_f32_e32 v22, s21, v22
	v_add_f32_e32 v22, s22, v22
	v_add_f32_e32 v22, s23, v22
	v_fmamk_f32 v22, v22, 0x3a000000, v20
	v_rsq_f32_e32 v24, v22
	s_nop 1
	v_pk_mul_f32 v[26:27], v[24:25], v[26:27] op_sel_hi:[0,1]
	v_pk_mul_f32 v[64:65], v[100:101], v[26:27]
	v_pk_mul_f32 v[28:29], v[24:25], v[28:29] op_sel_hi:[0,1]
	v_pk_mul_f32 v[66:67], v[102:103], v[28:29]
	global_store_dwordx4 v2, v[64:67], s[14:15] offset:-4096
	v_pk_mul_f32 v[30:31], v[24:25], v[30:31] op_sel_hi:[0,1]
	v_pk_mul_f32 v[68:69], v[104:105], v[30:31]
	v_pk_mul_f32 v[32:33], v[24:25], v[32:33] op_sel_hi:[0,1]
	v_pk_mul_f32 v[70:71], v[106:107], v[32:33]
	global_store_dwordx4 v2, v[68:71], s[14:15] offset:-3072
	v_pk_mul_f32 v[34:35], v[24:25], v[34:35] op_sel_hi:[0,1]
	v_pk_mul_f32 v[72:73], v[108:109], v[34:35]
	v_pk_mul_f32 v[36:37], v[24:25], v[36:37] op_sel_hi:[0,1]
	v_pk_mul_f32 v[74:75], v[110:111], v[36:37]
	global_store_dwordx4 v2, v[72:75], s[14:15] offset:-2048
	v_pk_mul_f32 v[38:39], v[24:25], v[38:39] op_sel_hi:[0,1]
	v_pk_mul_f32 v[76:77], v[112:113], v[38:39]
	v_pk_mul_f32 v[40:41], v[24:25], v[40:41] op_sel_hi:[0,1]
	v_pk_mul_f32 v[78:79], v[114:115], v[40:41]
	global_store_dwordx4 v2, v[76:79], s[14:15] offset:-1024
	v_pk_mul_f32 v[42:43], v[24:25], v[42:43] op_sel_hi:[0,1]
	v_pk_mul_f32 v[80:81], v[116:117], v[42:43]
	v_pk_mul_f32 v[44:45], v[24:25], v[44:45] op_sel_hi:[0,1]
	v_pk_mul_f32 v[82:83], v[118:119], v[44:45]
	global_store_dwordx4 v2, v[80:83], s[14:15] offset:0
	v_pk_mul_f32 v[46:47], v[24:25], v[46:47] op_sel_hi:[0,1]
	v_pk_mul_f32 v[84:85], v[120:121], v[46:47]
	v_pk_mul_f32 v[48:49], v[24:25], v[48:49] op_sel_hi:[0,1]
	v_pk_mul_f32 v[86:87], v[122:123], v[48:49]
	global_store_dwordx4 v2, v[84:87], s[14:15] offset:1024
	v_pk_mul_f32 v[50:51], v[24:25], v[50:51] op_sel_hi:[0,1]
	v_pk_mul_f32 v[88:89], v[124:125], v[50:51]
	v_pk_mul_f32 v[52:53], v[24:25], v[52:53] op_sel_hi:[0,1]
	v_pk_mul_f32 v[90:91], v[126:127], v[52:53]
	global_store_dwordx4 v2, v[88:91], s[14:15] offset:2048
	v_pk_mul_f32 v[54:55], v[24:25], v[54:55] op_sel_hi:[0,1]
	v_pk_mul_f32 v[92:93], v[128:129], v[54:55]
	v_pk_mul_f32 v[56:57], v[24:25], v[56:57] op_sel_hi:[0,1]
	v_pk_mul_f32 v[94:95], v[130:131], v[56:57]
	global_store_dwordx4 v2, v[92:95], s[14:15] offset:3072
	s_add_u32 s14, s14, s18
	s_addc_u32 s15, s15, s19
	s_cmpk_lt_i32 s0, 0x2000
	s_waitcnt vmcnt(8)
	s_cbranch_scc1 .Lfn_loop
